# s5_kc rewritten: 8 outputs per thread sharing the loads, run on the 128 workgroups without a K/V GEMM unit; dn scan 16 chunks per trip
# speedup vs baseline: 1.0078x; 1.0078x over previous
; DEVI int otid() { int t = threadIdx.x; asm volatile("" : "+v"(t)); return t; }
; DEVI int obid() { int t = blockIdx.x; asm volatile("" : "+s"(t)); return t; }
; DEVI void s5_kc(const Params& p) {
;     const float* apow = (const float*)(p.ws + OFF_APOW); const float* bb = (const float*)(p.ws + OFF_BB); float* kc = (float*)(p.ws + OFF_KC);
;     const int NE = 64 * 32 * 256, G2 = gridDim.x >> 1; const bool busy = obid() < G2; const int lo = busy ? (NE / 3) * 2 : 0, hi = busy ? NE : (NE / 3) * 2, w = busy ? obid() : obid() - G2;
;     for (int e = lo + w * 512 + otid(); e < hi; e += (gridDim.x - G2) * 512 * (busy ? 0 : 1) + G2 * 512 * (busy ? 1 : 0)) { const int h2 = e & 15, hh = (e >> 4) & 15, tau = (e >> 8) & 31, g = e >> 13; float s = 0.f;
;         for (int pp = 0; pp < 64; ++pp) { const size_t gp = (size_t)g * 64 + pp; const float ar = apow[(gp * 34 + tau) * 2], ai = apow[(gp * 34 + tau) * 2 + 1];
;             const float br = bb[(gp * 16 + h2) * 2], bi = bb[(gp * 16 + h2) * 2 + 1]; const float cr = p.in[23][((size_t)g * 16 + hh) * 64 + pp], ci = p.in[24][((size_t)g * 16 + hh) * 64 + pp];
;             const float xr = ar * br - ai * bi, xi = ar * bi + ai * br; s += cr * xr - ci * xi; }
;         kc[e] = s; }
; }
.LBB0_196:
	s_add_u32 s0, s20, 0x1d680000
	s_addc_u32 s1, s21, 0
	v_writelane_b32 v252, s0, 40
	s_nop 0
	v_writelane_b32 v252, s1, 41
	s_mov_b64 s[2:3], s[0:1]
	s_mov_b64 s[0:1], exec
	s_and_b64 vcc, exec, s[4:5]
	s_cbranch_vccnz .LBB0_201
	v_readlane_b32 s36, v251, 40
	v_readlane_b32 s37, v251, 41
	v_lshl_add_u32 v0, s9, 9, v154
	v_lshrrev_b32_e32 v1, 10, v0
	v_bfe_u32 v2, v0, 5, 5
	v_bfe_u32 v3, v0, 1, 4
	v_and_b32_e32 v4, 1, v0
	v_lshl_or_b32 v5, v1, 4, v3
	v_lshlrev_b32_e32 v5, 8, v5
	v_mul_u32_u24_e32 v6, 0x4400, v1
	v_lshl_add_u32 v6, v2, 3, v6
	v_lshlrev_b32_e32 v7, 13, v1
	v_lshl_or_b32 v7, v4, 6, v7
	v_lshlrev_b32_e32 v8, 5, v0
	s_add_u32 s10, s20, 0x1d880000
	s_addc_u32 s11, s21, 0
	s_add_u32 s12, s20, 0x1d9c0000
	s_addc_u32 s13, s21, 0
	v_mov_b32_e32 v10, 0
	v_mov_b32_e32 v11, 0
	v_mov_b32_e32 v12, 0
	v_mov_b32_e32 v13, 0
	v_mov_b32_e32 v14, 0
	v_mov_b32_e32 v15, 0
	v_mov_b32_e32 v16, 0
	v_mov_b32_e32 v17, 0
	s_mov_b32 s14, 16
.Lkc2_loop:
	global_load_dwordx4 v[56:59], v5, s[58:59]
	global_load_dwordx4 v[60:63], v5, s[36:37]
	global_load_dwordx2 v[64:65], v6, s[10:11]
	global_load_dwordx4 v[72:75], v7, s[12:13]
	global_load_dwordx4 v[76:79], v7, s[12:13] offset:16
	global_load_dwordx4 v[80:83], v7, s[12:13] offset:32
	global_load_dwordx4 v[84:87], v7, s[12:13] offset:48
	global_load_dwordx2 v[66:67], v6, s[10:11] offset:272
	global_load_dwordx4 v[88:91], v7, s[12:13] offset:128
	global_load_dwordx4 v[92:95], v7, s[12:13] offset:144
	global_load_dwordx4 v[96:99], v7, s[12:13] offset:160
	global_load_dwordx4 v[100:103], v7, s[12:13] offset:176
	global_load_dwordx2 v[68:69], v6, s[10:11] offset:544
	global_load_dwordx4 v[104:107], v7, s[12:13] offset:256
	global_load_dwordx4 v[108:111], v7, s[12:13] offset:272
	global_load_dwordx4 v[112:115], v7, s[12:13] offset:288
	global_load_dwordx4 v[116:119], v7, s[12:13] offset:304
	global_load_dwordx2 v[70:71], v6, s[10:11] offset:816
	global_load_dwordx4 v[120:123], v7, s[12:13] offset:384
	global_load_dwordx4 v[124:127], v7, s[12:13] offset:400
	global_load_dwordx4 v[128:131], v7, s[12:13] offset:416
	global_load_dwordx4 v[132:135], v7, s[12:13] offset:432
	v_add_u32_e32 v5, 16, v5
	v_add_u32_e32 v6, 0x440, v6
	v_add_u32_e32 v7, 0x200, v7
	s_waitcnt vmcnt(15)
	v_mov_b32_e32 v18, v56
	v_mov_b32_e32 v19, v60
	v_pk_mul_f32 v[26:27], v[64:65], v[72:73] op_sel:[1,1] op_sel_hi:[0,1]
	v_pk_mul_f32 v[20:21], v[64:65], v[74:75] op_sel:[1,1] op_sel_hi:[0,1]
	v_pk_fma_f32 v[28:29], v[64:65], v[72:73], v[26:27] neg_lo:[0,0,1] neg_hi:[0,0,1]
	v_pk_fma_f32 v[22:23], v[64:65], v[74:75], v[20:21] neg_lo:[0,0,1] neg_hi:[0,0,1]
	v_pk_fma_f32 v[26:27], v[64:65], v[72:73], v[26:27] op_sel_hi:[1,0,1]
	v_pk_fma_f32 v[20:21], v[64:65], v[74:75], v[20:21] op_sel_hi:[1,0,1]
	v_mov_b32_e32 v29, v27
	v_mov_b32_e32 v23, v21
	v_pk_mul_f32 v[26:27], v[18:19], v[28:29]
	v_pk_mul_f32 v[20:21], v[18:19], v[22:23]
	v_sub_f32_e32 v9, v26, v27
	v_sub_f32_e32 v24, v20, v21
	v_add_f32_e32 v10, v10, v9
	v_add_f32_e32 v11, v11, v24
	v_pk_mul_f32 v[26:27], v[64:65], v[76:77] op_sel:[1,1] op_sel_hi:[0,1]
	v_pk_mul_f32 v[20:21], v[64:65], v[78:79] op_sel:[1,1] op_sel_hi:[0,1]
	v_pk_fma_f32 v[28:29], v[64:65], v[76:77], v[26:27] neg_lo:[0,0,1] neg_hi:[0,0,1]
	v_pk_fma_f32 v[22:23], v[64:65], v[78:79], v[20:21] neg_lo:[0,0,1] neg_hi:[0,0,1]
	v_pk_fma_f32 v[26:27], v[64:65], v[76:77], v[26:27] op_sel_hi:[1,0,1]
	v_pk_fma_f32 v[20:21], v[64:65], v[78:79], v[20:21] op_sel_hi:[1,0,1]
	v_mov_b32_e32 v29, v27
	v_mov_b32_e32 v23, v21
	v_pk_mul_f32 v[26:27], v[18:19], v[28:29]
	v_pk_mul_f32 v[20:21], v[18:19], v[22:23]
	v_sub_f32_e32 v9, v26, v27
	v_sub_f32_e32 v24, v20, v21
	v_add_f32_e32 v12, v12, v9
	v_add_f32_e32 v13, v13, v24
	v_pk_mul_f32 v[26:27], v[64:65], v[80:81] op_sel:[1,1] op_sel_hi:[0,1]
	v_pk_mul_f32 v[20:21], v[64:65], v[82:83] op_sel:[1,1] op_sel_hi:[0,1]
	v_pk_fma_f32 v[28:29], v[64:65], v[80:81], v[26:27] neg_lo:[0,0,1] neg_hi:[0,0,1]
	v_pk_fma_f32 v[22:23], v[64:65], v[82:83], v[20:21] neg_lo:[0,0,1] neg_hi:[0,0,1]
	v_pk_fma_f32 v[26:27], v[64:65], v[80:81], v[26:27] op_sel_hi:[1,0,1]
	v_pk_fma_f32 v[20:21], v[64:65], v[82:83], v[20:21] op_sel_hi:[1,0,1]
	v_mov_b32_e32 v29, v27
	v_mov_b32_e32 v23, v21
	v_pk_mul_f32 v[26:27], v[18:19], v[28:29]
	v_pk_mul_f32 v[20:21], v[18:19], v[22:23]
	v_sub_f32_e32 v9, v26, v27
	v_sub_f32_e32 v24, v20, v21
	v_add_f32_e32 v14, v14, v9
	v_add_f32_e32 v15, v15, v24
	v_pk_mul_f32 v[26:27], v[64:65], v[84:85] op_sel:[1,1] op_sel_hi:[0,1]
	v_pk_mul_f32 v[20:21], v[64:65], v[86:87] op_sel:[1,1] op_sel_hi:[0,1]
	v_pk_fma_f32 v[28:29], v[64:65], v[84:85], v[26:27] neg_lo:[0,0,1] neg_hi:[0,0,1]
	v_pk_fma_f32 v[22:23], v[64:65], v[86:87], v[20:21] neg_lo:[0,0,1] neg_hi:[0,0,1]
	v_pk_fma_f32 v[26:27], v[64:65], v[84:85], v[26:27] op_sel_hi:[1,0,1]
	v_pk_fma_f32 v[20:21], v[64:65], v[86:87], v[20:21] op_sel_hi:[1,0,1]
	v_mov_b32_e32 v29, v27
	v_mov_b32_e32 v23, v21
	v_pk_mul_f32 v[26:27], v[18:19], v[28:29]
	v_pk_mul_f32 v[20:21], v[18:19], v[22:23]
	v_sub_f32_e32 v9, v26, v27
	v_sub_f32_e32 v24, v20, v21
	v_add_f32_e32 v16, v16, v9
	v_add_f32_e32 v17, v17, v24
	s_waitcnt vmcnt(10)
; DEVI void s5_kc(const Params& p) {
;     ...
;         for (int pp = 0; pp < 64; ++pp) { const size_t gp = (size_t)g * 64 + pp; const float ar = apow[(gp * 34 + tau) * 2], ai = apow[(gp * 34 + tau) * 2 + 1];
;             const float br = bb[(gp * 16 + h2) * 2], bi = bb[(gp * 16 + h2) * 2 + 1]; const float cr = p.in[23][((size_t)g * 16 + hh) * 64 + pp], ci = p.in[24][((size_t)g * 16 + hh) * 64 + pp];
;             const float xr = ar * br - ai * bi, xi = ar * bi + ai * br; s += cr * xr - ci * xi; }
	v_mov_b32_e32 v18, v57
	v_mov_b32_e32 v19, v61
	v_pk_mul_f32 v[26:27], v[66:67], v[88:89] op_sel:[1,1] op_sel_hi:[0,1]
	v_pk_mul_f32 v[20:21], v[66:67], v[90:91] op_sel:[1,1] op_sel_hi:[0,1]
	v_pk_fma_f32 v[28:29], v[66:67], v[88:89], v[26:27] neg_lo:[0,0,1] neg_hi:[0,0,1]
	v_pk_fma_f32 v[22:23], v[66:67], v[90:91], v[20:21] neg_lo:[0,0,1] neg_hi:[0,0,1]
	v_pk_fma_f32 v[26:27], v[66:67], v[88:89], v[26:27] op_sel_hi:[1,0,1]
	v_pk_fma_f32 v[20:21], v[66:67], v[90:91], v[20:21] op_sel_hi:[1,0,1]
	v_mov_b32_e32 v29, v27
	v_mov_b32_e32 v23, v21
	v_pk_mul_f32 v[26:27], v[18:19], v[28:29]
	v_pk_mul_f32 v[20:21], v[18:19], v[22:23]
	v_sub_f32_e32 v9, v26, v27
	v_sub_f32_e32 v24, v20, v21
	v_add_f32_e32 v10, v10, v9
	v_add_f32_e32 v11, v11, v24
	v_pk_mul_f32 v[26:27], v[66:67], v[92:93] op_sel:[1,1] op_sel_hi:[0,1]
	v_pk_mul_f32 v[20:21], v[66:67], v[94:95] op_sel:[1,1] op_sel_hi:[0,1]
	v_pk_fma_f32 v[28:29], v[66:67], v[92:93], v[26:27] neg_lo:[0,0,1] neg_hi:[0,0,1]
	v_pk_fma_f32 v[22:23], v[66:67], v[94:95], v[20:21] neg_lo:[0,0,1] neg_hi:[0,0,1]
	v_pk_fma_f32 v[26:27], v[66:67], v[92:93], v[26:27] op_sel_hi:[1,0,1]
	v_pk_fma_f32 v[20:21], v[66:67], v[94:95], v[20:21] op_sel_hi:[1,0,1]
	v_mov_b32_e32 v29, v27
	v_mov_b32_e32 v23, v21
	v_pk_mul_f32 v[26:27], v[18:19], v[28:29]
	v_pk_mul_f32 v[20:21], v[18:19], v[22:23]
	v_sub_f32_e32 v9, v26, v27
	v_sub_f32_e32 v24, v20, v21
	v_add_f32_e32 v12, v12, v9
	v_add_f32_e32 v13, v13, v24
	v_pk_mul_f32 v[26:27], v[66:67], v[96:97] op_sel:[1,1] op_sel_hi:[0,1]
	v_pk_mul_f32 v[20:21], v[66:67], v[98:99] op_sel:[1,1] op_sel_hi:[0,1]
	v_pk_fma_f32 v[28:29], v[66:67], v[96:97], v[26:27] neg_lo:[0,0,1] neg_hi:[0,0,1]
	v_pk_fma_f32 v[22:23], v[66:67], v[98:99], v[20:21] neg_lo:[0,0,1] neg_hi:[0,0,1]
	v_pk_fma_f32 v[26:27], v[66:67], v[96:97], v[26:27] op_sel_hi:[1,0,1]
	v_pk_fma_f32 v[20:21], v[66:67], v[98:99], v[20:21] op_sel_hi:[1,0,1]
	v_mov_b32_e32 v29, v27
	v_mov_b32_e32 v23, v21
	v_pk_mul_f32 v[26:27], v[18:19], v[28:29]
	v_pk_mul_f32 v[20:21], v[18:19], v[22:23]
	v_sub_f32_e32 v9, v26, v27
	v_sub_f32_e32 v24, v20, v21
	v_add_f32_e32 v14, v14, v9
	v_add_f32_e32 v15, v15, v24
	v_pk_mul_f32 v[26:27], v[66:67], v[100:101] op_sel:[1,1] op_sel_hi:[0,1]
	v_pk_mul_f32 v[20:21], v[66:67], v[102:103] op_sel:[1,1] op_sel_hi:[0,1]
	v_pk_fma_f32 v[28:29], v[66:67], v[100:101], v[26:27] neg_lo:[0,0,1] neg_hi:[0,0,1]
	v_pk_fma_f32 v[22:23], v[66:67], v[102:103], v[20:21] neg_lo:[0,0,1] neg_hi:[0,0,1]
	v_pk_fma_f32 v[26:27], v[66:67], v[100:101], v[26:27] op_sel_hi:[1,0,1]
	v_pk_fma_f32 v[20:21], v[66:67], v[102:103], v[20:21] op_sel_hi:[1,0,1]
	v_mov_b32_e32 v29, v27
	v_mov_b32_e32 v23, v21
	v_pk_mul_f32 v[26:27], v[18:19], v[28:29]
	v_pk_mul_f32 v[20:21], v[18:19], v[22:23]
	v_sub_f32_e32 v9, v26, v27
	v_sub_f32_e32 v24, v20, v21
	v_add_f32_e32 v16, v16, v9
	v_add_f32_e32 v17, v17, v24
	s_waitcnt vmcnt(5)
	v_mov_b32_e32 v18, v58
	v_mov_b32_e32 v19, v62
	v_pk_mul_f32 v[26:27], v[68:69], v[104:105] op_sel:[1,1] op_sel_hi:[0,1]
	v_pk_mul_f32 v[20:21], v[68:69], v[106:107] op_sel:[1,1] op_sel_hi:[0,1]
	v_pk_fma_f32 v[28:29], v[68:69], v[104:105], v[26:27] neg_lo:[0,0,1] neg_hi:[0,0,1]
	v_pk_fma_f32 v[22:23], v[68:69], v[106:107], v[20:21] neg_lo:[0,0,1] neg_hi:[0,0,1]
	v_pk_fma_f32 v[26:27], v[68:69], v[104:105], v[26:27] op_sel_hi:[1,0,1]
	v_pk_fma_f32 v[20:21], v[68:69], v[106:107], v[20:21] op_sel_hi:[1,0,1]
	v_mov_b32_e32 v29, v27
	v_mov_b32_e32 v23, v21
	v_pk_mul_f32 v[26:27], v[18:19], v[28:29]
	v_pk_mul_f32 v[20:21], v[18:19], v[22:23]
	v_sub_f32_e32 v9, v26, v27
	v_sub_f32_e32 v24, v20, v21
	v_add_f32_e32 v10, v10, v9
	v_add_f32_e32 v11, v11, v24
	v_pk_mul_f32 v[26:27], v[68:69], v[108:109] op_sel:[1,1] op_sel_hi:[0,1]
	v_pk_mul_f32 v[20:21], v[68:69], v[110:111] op_sel:[1,1] op_sel_hi:[0,1]
	v_pk_fma_f32 v[28:29], v[68:69], v[108:109], v[26:27] neg_lo:[0,0,1] neg_hi:[0,0,1]
	v_pk_fma_f32 v[22:23], v[68:69], v[110:111], v[20:21] neg_lo:[0,0,1] neg_hi:[0,0,1]
	v_pk_fma_f32 v[26:27], v[68:69], v[108:109], v[26:27] op_sel_hi:[1,0,1]
	v_pk_fma_f32 v[20:21], v[68:69], v[110:111], v[20:21] op_sel_hi:[1,0,1]
	v_mov_b32_e32 v29, v27
	v_mov_b32_e32 v23, v21
	v_pk_mul_f32 v[26:27], v[18:19], v[28:29]
	v_pk_mul_f32 v[20:21], v[18:19], v[22:23]
	v_sub_f32_e32 v9, v26, v27
	v_sub_f32_e32 v24, v20, v21
	v_add_f32_e32 v12, v12, v9
	v_add_f32_e32 v13, v13, v24
	v_pk_mul_f32 v[26:27], v[68:69], v[112:113] op_sel:[1,1] op_sel_hi:[0,1]
	v_pk_mul_f32 v[20:21], v[68:69], v[114:115] op_sel:[1,1] op_sel_hi:[0,1]
	v_pk_fma_f32 v[28:29], v[68:69], v[112:113], v[26:27] neg_lo:[0,0,1] neg_hi:[0,0,1]
	v_pk_fma_f32 v[22:23], v[68:69], v[114:115], v[20:21] neg_lo:[0,0,1] neg_hi:[0,0,1]
	v_pk_fma_f32 v[26:27], v[68:69], v[112:113], v[26:27] op_sel_hi:[1,0,1]
	v_pk_fma_f32 v[20:21], v[68:69], v[114:115], v[20:21] op_sel_hi:[1,0,1]
	v_mov_b32_e32 v29, v27
	v_mov_b32_e32 v23, v21
	v_pk_mul_f32 v[26:27], v[18:19], v[28:29]
	v_pk_mul_f32 v[20:21], v[18:19], v[22:23]
	v_sub_f32_e32 v9, v26, v27
	v_sub_f32_e32 v24, v20, v21
	v_add_f32_e32 v14, v14, v9
	v_add_f32_e32 v15, v15, v24
	v_pk_mul_f32 v[26:27], v[68:69], v[116:117] op_sel:[1,1] op_sel_hi:[0,1]
	v_pk_mul_f32 v[20:21], v[68:69], v[118:119] op_sel:[1,1] op_sel_hi:[0,1]
	v_pk_fma_f32 v[28:29], v[68:69], v[116:117], v[26:27] neg_lo:[0,0,1] neg_hi:[0,0,1]
	v_pk_fma_f32 v[22:23], v[68:69], v[118:119], v[20:21] neg_lo:[0,0,1] neg_hi:[0,0,1]
	v_pk_fma_f32 v[26:27], v[68:69], v[116:117], v[26:27] op_sel_hi:[1,0,1]
	v_pk_fma_f32 v[20:21], v[68:69], v[118:119], v[20:21] op_sel_hi:[1,0,1]
	v_mov_b32_e32 v29, v27
	v_mov_b32_e32 v23, v21
	v_pk_mul_f32 v[26:27], v[18:19], v[28:29]
	v_pk_mul_f32 v[20:21], v[18:19], v[22:23]
	v_sub_f32_e32 v9, v26, v27
	v_sub_f32_e32 v24, v20, v21
	v_add_f32_e32 v16, v16, v9
	v_add_f32_e32 v17, v17, v24
	s_waitcnt vmcnt(0)
; DEVI void s5_kc(const Params& p) {
;     ...
;         for (int pp = 0; pp < 64; ++pp) { const size_t gp = (size_t)g * 64 + pp; const float ar = apow[(gp * 34 + tau) * 2], ai = apow[(gp * 34 + tau) * 2 + 1];
;             const float br = bb[(gp * 16 + h2) * 2], bi = bb[(gp * 16 + h2) * 2 + 1]; const float cr = p.in[23][((size_t)g * 16 + hh) * 64 + pp], ci = p.in[24][((size_t)g * 16 + hh) * 64 + pp];
;             const float xr = ar * br - ai * bi, xi = ar * bi + ai * br; s += cr * xr - ci * xi; }
;         kc[e] = s; }
	v_mov_b32_e32 v18, v59
	v_mov_b32_e32 v19, v63
	v_pk_mul_f32 v[26:27], v[70:71], v[120:121] op_sel:[1,1] op_sel_hi:[0,1]
	v_pk_mul_f32 v[20:21], v[70:71], v[122:123] op_sel:[1,1] op_sel_hi:[0,1]
	v_pk_fma_f32 v[28:29], v[70:71], v[120:121], v[26:27] neg_lo:[0,0,1] neg_hi:[0,0,1]
	v_pk_fma_f32 v[22:23], v[70:71], v[122:123], v[20:21] neg_lo:[0,0,1] neg_hi:[0,0,1]
	v_pk_fma_f32 v[26:27], v[70:71], v[120:121], v[26:27] op_sel_hi:[1,0,1]
	v_pk_fma_f32 v[20:21], v[70:71], v[122:123], v[20:21] op_sel_hi:[1,0,1]
	v_mov_b32_e32 v29, v27
	v_mov_b32_e32 v23, v21
	v_pk_mul_f32 v[26:27], v[18:19], v[28:29]
	v_pk_mul_f32 v[20:21], v[18:19], v[22:23]
	v_sub_f32_e32 v9, v26, v27
	v_sub_f32_e32 v24, v20, v21
	v_add_f32_e32 v10, v10, v9
	v_add_f32_e32 v11, v11, v24
	v_pk_mul_f32 v[26:27], v[70:71], v[124:125] op_sel:[1,1] op_sel_hi:[0,1]
	v_pk_mul_f32 v[20:21], v[70:71], v[126:127] op_sel:[1,1] op_sel_hi:[0,1]
	v_pk_fma_f32 v[28:29], v[70:71], v[124:125], v[26:27] neg_lo:[0,0,1] neg_hi:[0,0,1]
	v_pk_fma_f32 v[22:23], v[70:71], v[126:127], v[20:21] neg_lo:[0,0,1] neg_hi:[0,0,1]
	v_pk_fma_f32 v[26:27], v[70:71], v[124:125], v[26:27] op_sel_hi:[1,0,1]
	v_pk_fma_f32 v[20:21], v[70:71], v[126:127], v[20:21] op_sel_hi:[1,0,1]
	v_mov_b32_e32 v29, v27
	v_mov_b32_e32 v23, v21
	v_pk_mul_f32 v[26:27], v[18:19], v[28:29]
	v_pk_mul_f32 v[20:21], v[18:19], v[22:23]
	v_sub_f32_e32 v9, v26, v27
	v_sub_f32_e32 v24, v20, v21
	v_add_f32_e32 v12, v12, v9
	v_add_f32_e32 v13, v13, v24
	v_pk_mul_f32 v[26:27], v[70:71], v[128:129] op_sel:[1,1] op_sel_hi:[0,1]
	v_pk_mul_f32 v[20:21], v[70:71], v[130:131] op_sel:[1,1] op_sel_hi:[0,1]
	v_pk_fma_f32 v[28:29], v[70:71], v[128:129], v[26:27] neg_lo:[0,0,1] neg_hi:[0,0,1]
	v_pk_fma_f32 v[22:23], v[70:71], v[130:131], v[20:21] neg_lo:[0,0,1] neg_hi:[0,0,1]
	v_pk_fma_f32 v[26:27], v[70:71], v[128:129], v[26:27] op_sel_hi:[1,0,1]
	v_pk_fma_f32 v[20:21], v[70:71], v[130:131], v[20:21] op_sel_hi:[1,0,1]
	v_mov_b32_e32 v29, v27
	v_mov_b32_e32 v23, v21
	v_pk_mul_f32 v[26:27], v[18:19], v[28:29]
	v_pk_mul_f32 v[20:21], v[18:19], v[22:23]
	v_sub_f32_e32 v9, v26, v27
	v_sub_f32_e32 v24, v20, v21
	v_add_f32_e32 v14, v14, v9
	v_add_f32_e32 v15, v15, v24
	v_pk_mul_f32 v[26:27], v[70:71], v[132:133] op_sel:[1,1] op_sel_hi:[0,1]
	v_pk_mul_f32 v[20:21], v[70:71], v[134:135] op_sel:[1,1] op_sel_hi:[0,1]
	v_pk_fma_f32 v[28:29], v[70:71], v[132:133], v[26:27] neg_lo:[0,0,1] neg_hi:[0,0,1]
	v_pk_fma_f32 v[22:23], v[70:71], v[134:135], v[20:21] neg_lo:[0,0,1] neg_hi:[0,0,1]
	v_pk_fma_f32 v[26:27], v[70:71], v[132:133], v[26:27] op_sel_hi:[1,0,1]
	v_pk_fma_f32 v[20:21], v[70:71], v[134:135], v[20:21] op_sel_hi:[1,0,1]
	v_mov_b32_e32 v29, v27
	v_mov_b32_e32 v23, v21
	v_pk_mul_f32 v[26:27], v[18:19], v[28:29]
	v_pk_mul_f32 v[20:21], v[18:19], v[22:23]
	v_sub_f32_e32 v9, v26, v27
	v_sub_f32_e32 v24, v20, v21
	v_add_f32_e32 v16, v16, v9
	v_add_f32_e32 v17, v17, v24
	s_sub_i32 s14, s14, 1
	s_cmp_lg_u32 s14, 0
	s_cbranch_scc1 .Lkc2_loop
	global_store_dwordx4 v8, v[10:13], s[2:3]
	global_store_dwordx4 v8, v[14:17], s[2:3] offset:16

; DEVI void mix_scan_phase(const MixArgs a, bool with_n) {
;     ...
;     if (with_n) for (int e = gt; e < 16 * 128; e += nthr) { const int dk = e & 127, bh = e >> 7; float run = 0.f;
;         for (int c = 0; c < NCH; ++c) { const size_t o = ((size_t)bh * NCH + c) * 128 + dk; const float x = a.dn[o], d = a.dec[o]; a.dn[o] = run; run = d * run + x; } }
.LBB0_632:
	v_lshl_add_u64 v[6:7], v[2:3], 0, s[6:7]
	v_add_co_u32_e32 v10, vcc, 0x1d580000, v6
	s_add_u32 s6, s6, 0x2000
	s_nop 0
	v_addc_co_u32_e32 v11, vcc, 0, v7, vcc
	v_add_co_u32_e32 v6, vcc, 0x1d600000, v6
	s_addc_u32 s7, s7, 0
	s_nop 0
	v_addc_co_u32_e32 v7, vcc, 0, v7, vcc
	v_add_co_u32_e32 v142, vcc, 0x1000, v10
	s_nop 1
	v_addc_co_u32_e32 v143, vcc, 0, v11, vcc
	v_add_co_u32_e32 v144, vcc, 0x1000, v6
	s_nop 1
	v_addc_co_u32_e32 v145, vcc, 0, v7, vcc
	global_load_dword v60, v[10:11], off
	global_load_dword v126, v[6:7], off
	global_load_dword v61, v[10:11], off offset:512
	global_load_dword v127, v[6:7], off offset:512
	global_load_dword v62, v[10:11], off offset:1024
	global_load_dword v128, v[6:7], off offset:1024
	global_load_dword v63, v[10:11], off offset:1536
	global_load_dword v129, v[6:7], off offset:1536
	global_load_dword v64, v[10:11], off offset:2048
	global_load_dword v130, v[6:7], off offset:2048
	global_load_dword v65, v[10:11], off offset:2560
	global_load_dword v131, v[6:7], off offset:2560
	global_load_dword v66, v[10:11], off offset:3072
	global_load_dword v132, v[6:7], off offset:3072
	global_load_dword v67, v[10:11], off offset:3584
	global_load_dword v133, v[6:7], off offset:3584
	global_load_dword v68, v[142:143], off
	global_load_dword v134, v[144:145], off
	global_load_dword v69, v[142:143], off offset:512
	global_load_dword v135, v[144:145], off offset:512
	global_load_dword v70, v[142:143], off offset:1024
	global_load_dword v136, v[144:145], off offset:1024
	global_load_dword v71, v[142:143], off offset:1536
	global_load_dword v137, v[144:145], off offset:1536
	global_load_dword v72, v[142:143], off offset:2048
	global_load_dword v138, v[144:145], off offset:2048
	global_load_dword v73, v[142:143], off offset:2560
	global_load_dword v139, v[144:145], off offset:2560
	global_load_dword v74, v[142:143], off offset:3072
	global_load_dword v140, v[144:145], off offset:3072
	global_load_dword v75, v[142:143], off offset:3584
	global_load_dword v141, v[144:145], off offset:3584
	global_store_dword v[10:11], v4, off
	s_waitcnt vmcnt(31)
	v_fmac_f32_e32 v60, v4, v126
	global_store_dword v[10:11], v60, off offset:512
	s_waitcnt vmcnt(30)
	v_fmac_f32_e32 v61, v60, v127
	global_store_dword v[10:11], v61, off offset:1024
	s_waitcnt vmcnt(29)
	v_fmac_f32_e32 v62, v61, v128
	global_store_dword v[10:11], v62, off offset:1536
	s_waitcnt vmcnt(28)
	v_fmac_f32_e32 v63, v62, v129
	global_store_dword v[10:11], v63, off offset:2048
	s_waitcnt vmcnt(27)
	v_fmac_f32_e32 v64, v63, v130
	global_store_dword v[10:11], v64, off offset:2560
	s_waitcnt vmcnt(26)
	v_fmac_f32_e32 v65, v64, v131
	global_store_dword v[10:11], v65, off offset:3072
	s_waitcnt vmcnt(25)
	v_fmac_f32_e32 v66, v65, v132
	global_store_dword v[10:11], v66, off offset:3584
	s_waitcnt vmcnt(24)
	v_fmac_f32_e32 v67, v66, v133
	global_store_dword v[142:143], v67, off
	s_waitcnt vmcnt(23)
	v_fmac_f32_e32 v68, v67, v134
	global_store_dword v[142:143], v68, off offset:512
	s_waitcnt vmcnt(22)
	v_fmac_f32_e32 v69, v68, v135
	global_store_dword v[142:143], v69, off offset:1024
	s_waitcnt vmcnt(21)
	v_fmac_f32_e32 v70, v69, v136
	global_store_dword v[142:143], v70, off offset:1536
	s_waitcnt vmcnt(20)
	v_fmac_f32_e32 v71, v70, v137
	global_store_dword v[142:143], v71, off offset:2048
	s_waitcnt vmcnt(19)
	v_fmac_f32_e32 v72, v71, v138
	global_store_dword v[142:143], v72, off offset:2560
	s_waitcnt vmcnt(18)
	v_fmac_f32_e32 v73, v72, v139
	global_store_dword v[142:143], v73, off offset:3072
	s_waitcnt vmcnt(17)
	v_fmac_f32_e32 v74, v73, v140
	global_store_dword v[142:143], v74, off offset:3584
	s_waitcnt vmcnt(16)
	v_fmac_f32_e32 v75, v74, v141
	v_mov_b32_e32 v4, v75
	s_cmpk_eq_u32 s6, 0x8000
	s_cbranch_scc0 .LBB0_632
	v_add_u32_e32 v16, s40, v16
	s_movk_i32 s0, 0x7ff
	v_cmp_lt_i32_e32 vcc, s0, v16
	s_or_b64 s[4:5], vcc, s[4:5]
	s_andn2_b64 exec, exec, s[4:5]
	s_cbranch_execnz .LBB0_631
